# conv_win: 32 row loads + 2 column-max loads in flight with counted waits (was 16 serialized load pairs); LN1 f32 path and LN2 row loops: waits no longer drain the row's own prefetch/stores
# speedup vs baseline: 1.0167x; 1.0032x over previous
; template <int MODE, bool ROUTE, int H8> ...
;     ...
;         unsigned wq0 = 0u, wq1 = 0u;
;         LN_LOAD(0);
.LBB0_835:
	s_lshl_b64 s[10:11], s[2:3], 12
	s_andn2_b64 vcc, exec, s[8:9]
	v_lshl_add_u64 v[120:121], v[64:65], 0, s[10:11]
	s_cbranch_vccnz .LBB0_837
	global_load_dwordx4 v[88:91], v[120:121], off nt
	v_mov_b64_e32 v[138:139], v[110:111]

; template <int MODE, bool ROUTE, int H8> ...
;     ...
;         unsigned wq0 = 0u, wq1 = 0u;
;         LN_LOAD(0);
.LBB0_840:
	global_load_dwordx4 v[84:87], v[120:121], off offset:1024 nt
	v_mov_b64_e32 v[140:141], v[112:113]

; template <int MODE, bool ROUTE, int H8> ...
;     ...
;         unsigned wq0 = 0u, wq1 = 0u;
;         LN_LOAD(0);
.LBB0_844:
	global_load_dwordx4 v[80:83], v[120:121], off offset:2048 nt
	v_mov_b64_e32 v[142:143], v[114:115]

; template <int MODE, bool ROUTE, int H8> ...
;     ...
;         unsigned wq0 = 0u, wq1 = 0u;
;         LN_LOAD(0);
.LBB0_848:
	global_load_dwordx4 v[76:79], v[120:121], off offset:3072 nt
	v_mov_b64_e32 v[148:149], v[116:117]

; template <int MODE, bool ROUTE, int H8> ...
;     ...
;             if (r + 1 < 32) LN_LOAD(r + 1);
.LBB0_853:
	s_lshl_b64 s[24:25], s[2:3], 12
	v_lshl_add_u64 v[144:145], v[64:65], 0, s[24:25]
	s_andn2_b64 vcc, exec, s[10:11]
	v_mov_b32_e32 v92, v88
	v_mov_b32_e32 v93, v89
	v_mov_b32_e32 v94, v90
	v_mov_b32_e32 v95, v91
	s_cbranch_vccnz .LBB0_855
	global_load_dwordx4 v[92:95], v[144:145], off nt
	v_mov_b64_e32 v[110:111], v[138:139]

; template <int MODE, bool ROUTE, int H8> ...
;     ...
;             if (r + 1 < 32) LN_LOAD(r + 1);
.LBB0_857:
	s_andn2_b64 vcc, exec, s[2:3]
	v_mov_b32_e32 v96, v84
	v_mov_b32_e32 v97, v85
	v_mov_b32_e32 v98, v86
	v_mov_b32_e32 v99, v87
	s_cbranch_vccnz .LBB0_859
	global_load_dwordx4 v[96:99], v[144:145], off offset:1024 nt
	v_mov_b64_e32 v[112:113], v[140:141]

; template <int MODE, bool ROUTE, int H8> ...
;     ...
;             if (r + 1 < 32) LN_LOAD(r + 1);
.LBB0_861:
	s_andn2_b64 vcc, exec, s[2:3]
	v_mov_b32_e32 v100, v80
	v_mov_b32_e32 v101, v81
	v_mov_b32_e32 v102, v82
	v_mov_b32_e32 v103, v83
	s_cbranch_vccnz .LBB0_863
	global_load_dwordx4 v[100:103], v[144:145], off offset:2048 nt
	v_mov_b64_e32 v[114:115], v[142:143]

; template <int MODE, bool ROUTE, int H8> ...
;     ...
;             if (r + 1 < 32) LN_LOAD(r + 1);
.LBB0_865:
	s_andn2_b64 vcc, exec, s[2:3]
	v_mov_b32_e32 v76, v12
	v_mov_b32_e32 v77, v13
	v_mov_b32_e32 v78, v14
	v_mov_b32_e32 v79, v15
	s_cbranch_vccnz .LBB0_867
	global_load_dwordx4 v[76:79], v[144:145], off offset:3072 nt
	v_mov_b64_e32 v[116:117], v[148:149]

; template <int MODE, bool ROUTE, int H8> ...
;     ...
;         unsigned wq0 = 0u, wq1 = 0u;
;         LN_LOAD(0);
;         for (int r = 0; r < 32; ++r) {
;             const int row = row0 + r;
;             f32x4 v[4]; float s = 0.f;
;             float w0 = 1.f, w1 = 0.f;
;             if (MODE == 1) { w0 = __builtin_bit_cast(float, wq0); w1 = __builtin_bit_cast(float, wq1); }
; #pragma unroll
;             for (int jj = 0; jj < 4; ++jj) {
;                 f32x4 x = xq[jj];
;                 if (xin16) x = __builtin_convertvector(__builtin_bit_cast(f16x4_t, xhq[jj]), f32x4);
;                 f32x4 y;
;                 if (MODE == 0) { const u32x2 yw = yq0[jj]; y = (f32x4){bflo(yw.x), bfhi(yw.x), bflo(yw.y), bfhi(yw.y)}; }
;                 else { const u32x2 ya = yq0[jj], yb = yq1[jj];
;                     y = (f32x4){bflo(ya.x), bfhi(ya.x), bflo(ya.y), bfhi(ya.y)} * w0 + (f32x4){bflo(yb.x), bfhi(yb.x), bflo(yb.y), bfhi(yb.y)} * w1; }
;                 v[jj] = x * ALPHA + gt[jj] * y;
;                 s += (v[jj][0] + v[jj][1]) + (v[jj][2] + v[jj][3]);
;             }
;             if (r + 1 < 32) LN_LOAD(r + 1);
.Lmy_ln2m_tail9:
	s_or_b64 exec, exec, s[24:25]
	s_add_i32 s56, s56, 1
	s_cmp_eq_u32 s56, 32
	s_waitcnt vmcnt(18)
	v_mov_b64_e32 v[84:85], v[132:133]
	v_mov_b64_e32 v[92:93], v[130:131]
	v_mov_b64_e32 v[88:89], v[128:129]
	v_mov_b64_e32 v[152:153], v[126:127]
	s_waitcnt vmcnt(14)
	v_mov_b64_e32 v[86:87], v[134:135]
	v_mov_b64_e32 v[94:95], v[136:137]
	v_mov_b64_e32 v[90:91], v[138:139]
	v_mov_b64_e32 v[154:155], v[140:141]
	s_waitcnt vmcnt(10)
	v_mov_b64_e32 v[96:97], v[142:143]
	v_mov_b64_e32 v[156:157], v[144:145]
	v_mov_b64_e32 v[158:159], v[146:147]
	v_mov_b64_e32 v[160:161], v[148:149]
	s_waitcnt vmcnt(9)
	v_mov_b64_e32 v[98:99], v[150:151]
	s_cbranch_scc1 .LBB0_1228
	s_branch .LBB0_1240
.Lmy_ln2m_tail4:
	s_add_i32 s56, s56, 1
	s_cmp_eq_u32 s56, 32
	s_waitcnt vmcnt(13)
	v_mov_b64_e32 v[84:85], v[132:133]
	v_mov_b64_e32 v[92:93], v[130:131]
	v_mov_b64_e32 v[88:89], v[128:129]
	v_mov_b64_e32 v[152:153], v[126:127]
	s_waitcnt vmcnt(9)
	v_mov_b64_e32 v[86:87], v[134:135]
	v_mov_b64_e32 v[94:95], v[136:137]
	v_mov_b64_e32 v[90:91], v[138:139]
	v_mov_b64_e32 v[154:155], v[140:141]
	s_waitcnt vmcnt(5)
	v_mov_b64_e32 v[96:97], v[142:143]
	v_mov_b64_e32 v[156:157], v[144:145]
	v_mov_b64_e32 v[158:159], v[146:147]
	v_mov_b64_e32 v[160:161], v[148:149]
	s_waitcnt vmcnt(4)
	v_mov_b64_e32 v[98:99], v[150:151]
	s_cbranch_scc1 .LBB0_1228
	s_branch .LBB0_1240

; template <int MODE, bool ROUTE, int H8> ...
;     ...
;         unsigned wq0 = 0u, wq1 = 0u;
;         LN_LOAD(0);
;         for (int r = 0; r < 32; ++r) {
;             const int row = row0 + r;
;             f32x4 v[4]; float s = 0.f;
;             float w0 = 1.f, w1 = 0.f;
;             if (MODE == 1) { w0 = __builtin_bit_cast(float, wq0); w1 = __builtin_bit_cast(float, wq1); }
; #pragma unroll
;             for (int jj = 0; jj < 4; ++jj) {
;                 f32x4 x = xq[jj];
;                 if (xin16) x = __builtin_convertvector(__builtin_bit_cast(f16x4_t, xhq[jj]), f32x4);
;                 f32x4 y;
;                 if (MODE == 0) { const u32x2 yw = yq0[jj]; y = (f32x4){bflo(yw.x), bfhi(yw.x), bflo(yw.y), bfhi(yw.y)}; }
;                 else { const u32x2 ya = yq0[jj], yb = yq1[jj];
;                     y = (f32x4){bflo(ya.x), bfhi(ya.x), bflo(ya.y), bfhi(ya.y)} * w0 + (f32x4){bflo(yb.x), bfhi(yb.x), bflo(yb.y), bfhi(yb.y)} * w1; }
;                 v[jj] = x * ALPHA + gt[jj] * y;
;                 s += (v[jj][0] + v[jj][1]) + (v[jj][2] + v[jj][3]);
;             }
;             if (r + 1 < 32) LN_LOAD(r + 1);
.Lmy_ln2d_tail9:
	s_or_b64 exec, exec, s[2:3]
	s_add_i32 s42, s42, 1
	s_cmp_eq_u32 s42, 32
	s_waitcnt vmcnt(13)
	v_mov_b64_e32 v[84:85], v[132:133]
	v_mov_b64_e32 v[92:93], v[130:131]
	v_mov_b64_e32 v[88:89], v[128:129]
	v_mov_b64_e32 v[96:97], v[126:127]
	s_waitcnt vmcnt(9)
	v_mov_b64_e32 v[86:87], v[134:135]
	v_mov_b64_e32 v[94:95], v[136:137]
	v_mov_b64_e32 v[90:91], v[138:139]
	v_mov_b64_e32 v[98:99], v[140:141]
	s_cbranch_scc1 .LBB0_1266
	s_branch .LBB0_1278
.Lmy_ln2d_tail4:
	s_add_i32 s42, s42, 1
	s_cmp_eq_u32 s42, 32
	s_waitcnt vmcnt(8)
	v_mov_b64_e32 v[84:85], v[132:133]
	v_mov_b64_e32 v[92:93], v[130:131]
	v_mov_b64_e32 v[88:89], v[128:129]
	v_mov_b64_e32 v[96:97], v[126:127]
	s_waitcnt vmcnt(4)
	v_mov_b64_e32 v[86:87], v[134:135]
	v_mov_b64_e32 v[94:95], v[136:137]
	v_mov_b64_e32 v[90:91], v[138:139]
	v_mov_b64_e32 v[98:99], v[140:141]
	s_cbranch_scc1 .LBB0_1266
	s_branch .LBB0_1278

; #define GAS __attribute__((address_space(1)))
; #define LAS __attribute__((address_space(3)))
; #define LDS_WAIT() asm volatile("s_waitcnt lgkmcnt(0)" ::: "memory")
; __device__ __forceinline__ void quant8_item(const float* W, int K, int N, signed char* WT, const gu32* wmax, LAS float* scr, int item, int lane) {
;     const int nblk = N / 32, kb = item / nblk, nb = item % nblk, k0 = 64 * kb, n0 = 32 * nb;
; #pragma unroll
;     for (int i = 0; i < 32; ++i) { const int kk = 2 * i + (lane >> 5); scr[kk * 33 + (lane & 31)] = W[(size_t)(k0 + kk) * N + n0 + (lane & 31)]; }
;     LDS_WAIT(); asm volatile("" ::: "memory");
;     const int c = lane & 3;
; #pragma unroll
;     for (int j = 0; j < 2; ++j) { const int n = (lane >> 2) + 16 * j; const LAS float* sp = scr + (16 * c) * 33 + n;
;         const float am = __builtin_bit_cast(float, __hip_atomic_load((unsigned*)(wmax + n0 + n), RLX_AGENT));
;         const float inv = 127.0f / fmaxf(am, 1e-30f);
;         unsigned w[4];
; #pragma unroll
;         for (int q = 0; q < 4; ++q) { unsigned pk = 0;
; #pragma unroll
;             for (int i = 0; i < 4; ++i) pk |= ((unsigned)(int)rintf(sp[(4 * q + i) * 33] * inv) & 0xffu) << (8 * i);
;             w[q] = pk; }
;         *(GAS u32x4*)(WT + (size_t)(n0 + n) * K + k0 + 16 * c) = (u32x4){w[0], w[1], w[2], w[3]}; }
;     LDS_WAIT(); asm volatile("" ::: "memory");
; }
.LBB0_1354:
	s_mul_hi_i32 s0, s6, 0x92492493
	s_add_i32 s0, s0, s6
	s_lshr_b32 s1, s0, 31
	s_ashr_i32 s0, s0, 6
	s_add_i32 s0, s0, s1
	s_lshl_b32 s2, s0, 6
	s_mulk_i32 s0, 0xf200
	s_add_i32 s0, s10, s0
	s_ashr_i32 s1, s0, 31
	s_lshl_b64 s[8:9], s[0:1], 2
	v_lshl_add_u64 v[2:3], v[6:7], 0, s[8:9]
	v_or_b32_e32 v4, s2, v20
	v_mad_i64_i32 v[4:5], s[12:13], v4, s4, v[2:3]
	global_load_dword v56, v[4:5], off
	v_or_b32_e32 v4, s2, v21
	v_mad_i64_i32 v[4:5], s[12:13], v4, s4, v[2:3]
	global_load_dword v57, v[4:5], off
	v_lshl_add_u64 v[14:15], v[10:11], 0, s[8:9]
	s_ashr_i32 s3, s2, 31
	v_add_u32_e32 v55, 0x400, v53
	s_add_i32 s6, s6, s7
	s_add_i32 s10, s10, s11
	s_cmpk_lt_i32 s6, 0x700
	v_or_b32_e32 v4, s2, v22
	v_mad_i64_i32 v[4:5], s[12:13], v4, s4, v[2:3]
	global_load_dword v58, v[4:5], off
	v_or_b32_e32 v4, s2, v23
	v_mad_i64_i32 v[4:5], s[12:13], v4, s4, v[2:3]
	global_load_dword v59, v[4:5], off
	v_or_b32_e32 v4, s2, v24
	v_mad_i64_i32 v[4:5], s[12:13], v4, s4, v[2:3]
	global_load_dword v60, v[4:5], off
	v_or_b32_e32 v4, s2, v25
	v_mad_i64_i32 v[4:5], s[12:13], v4, s4, v[2:3]
	global_load_dword v61, v[4:5], off
	v_or_b32_e32 v4, s2, v26
	v_mad_i64_i32 v[4:5], s[12:13], v4, s4, v[2:3]
	global_load_dword v62, v[4:5], off
	v_or_b32_e32 v4, s2, v27
	v_mad_i64_i32 v[4:5], s[12:13], v4, s4, v[2:3]
	global_load_dword v63, v[4:5], off
	v_or_b32_e32 v4, s2, v28
	v_mad_i64_i32 v[4:5], s[12:13], v4, s4, v[2:3]
	global_load_dword v64, v[4:5], off
	v_or_b32_e32 v4, s2, v29
	v_mad_i64_i32 v[4:5], s[12:13], v4, s4, v[2:3]
	global_load_dword v65, v[4:5], off
	v_or_b32_e32 v4, s2, v30
	v_mad_i64_i32 v[4:5], s[12:13], v4, s4, v[2:3]
	global_load_dword v68, v[4:5], off
	v_or_b32_e32 v4, s2, v31
	v_mad_i64_i32 v[4:5], s[12:13], v4, s4, v[2:3]
	global_load_dword v69, v[4:5], off
	v_or_b32_e32 v4, s2, v32
	v_mad_i64_i32 v[4:5], s[12:13], v4, s4, v[2:3]
	global_load_dword v70, v[4:5], off
	v_or_b32_e32 v4, s2, v33
	v_mad_i64_i32 v[4:5], s[12:13], v4, s4, v[2:3]
	global_load_dword v71, v[4:5], off
	v_or_b32_e32 v4, s2, v34
	v_mad_i64_i32 v[4:5], s[12:13], v4, s4, v[2:3]
	global_load_dword v72, v[4:5], off
	v_or_b32_e32 v4, s2, v35
	v_mad_i64_i32 v[4:5], s[12:13], v4, s4, v[2:3]
	global_load_dword v73, v[4:5], off
	v_or_b32_e32 v4, s2, v36
	v_mad_i64_i32 v[4:5], s[12:13], v4, s4, v[2:3]
	global_load_dword v74, v[4:5], off
	v_or_b32_e32 v4, s2, v37
	v_mad_i64_i32 v[4:5], s[12:13], v4, s4, v[2:3]
	global_load_dword v75, v[4:5], off
	v_or_b32_e32 v4, s2, v38
	v_mad_i64_i32 v[4:5], s[12:13], v4, s4, v[2:3]
	global_load_dword v76, v[4:5], off
	v_or_b32_e32 v4, s2, v39
	v_mad_i64_i32 v[4:5], s[12:13], v4, s4, v[2:3]
	global_load_dword v77, v[4:5], off
	v_or_b32_e32 v4, s2, v40
	v_mad_i64_i32 v[4:5], s[12:13], v4, s4, v[2:3]
	global_load_dword v78, v[4:5], off
	v_or_b32_e32 v4, s2, v41
	v_mad_i64_i32 v[4:5], s[12:13], v4, s4, v[2:3]
	global_load_dword v79, v[4:5], off
	v_or_b32_e32 v4, s2, v42
	v_mad_i64_i32 v[4:5], s[12:13], v4, s4, v[2:3]
	global_load_dword v80, v[4:5], off
	v_or_b32_e32 v4, s2, v43
	v_mad_i64_i32 v[4:5], s[12:13], v4, s4, v[2:3]
	global_load_dword v81, v[4:5], off
	v_or_b32_e32 v4, s2, v44
	v_mad_i64_i32 v[4:5], s[12:13], v4, s4, v[2:3]
	global_load_dword v82, v[4:5], off
	v_or_b32_e32 v4, s2, v45
	v_mad_i64_i32 v[4:5], s[12:13], v4, s4, v[2:3]
	global_load_dword v83, v[4:5], off
	v_or_b32_e32 v4, s2, v46
	v_mad_i64_i32 v[4:5], s[12:13], v4, s4, v[2:3]
	global_load_dword v84, v[4:5], off
	v_or_b32_e32 v4, s2, v47
	v_mad_i64_i32 v[4:5], s[12:13], v4, s4, v[2:3]
	global_load_dword v85, v[4:5], off
	v_or_b32_e32 v4, s2, v48
	v_mad_i64_i32 v[4:5], s[12:13], v4, s4, v[2:3]
	global_load_dword v86, v[4:5], off
	v_or_b32_e32 v4, s2, v49
	v_mad_i64_i32 v[4:5], s[12:13], v4, s4, v[2:3]
	global_load_dword v87, v[4:5], off
	v_or_b32_e32 v4, s2, v50
	v_mad_i64_i32 v[4:5], s[12:13], v4, s4, v[2:3]
	global_load_dword v88, v[4:5], off
	v_or_b32_e32 v5, s2, v51
	v_mad_i64_i32 v[2:3], s[12:13], v5, s4, v[2:3]
	global_load_dword v89, v[2:3], off
	global_load_dword v90, v[14:15], off sc1
	global_load_dword v91, v[14:15], off offset:64 sc1
	v_add_u32_e32 v13, 0x400, v54
	s_waitcnt vmcnt(32)
	ds_write2_b32 v54, v56, v57 offset1:66
	s_waitcnt vmcnt(30)
	ds_write2_b32 v54, v58, v59 offset0:132 offset1:198
	s_waitcnt vmcnt(28)
	ds_write2_b32 v13, v60, v61 offset0:8 offset1:74
	s_waitcnt vmcnt(26)
	ds_write2_b32 v13, v62, v63 offset0:140 offset1:206
	v_add_u32_e32 v13, 0x800, v54
	s_waitcnt vmcnt(24)
	ds_write2_b32 v13, v64, v65 offset0:16 offset1:82
	s_waitcnt vmcnt(22)
	ds_write2_b32 v13, v68, v69 offset0:148 offset1:214
	v_add_u32_e32 v13, 0xc00, v54
	s_waitcnt vmcnt(20)
	ds_write2_b32 v13, v70, v71 offset0:24 offset1:90
	s_waitcnt vmcnt(18)
	ds_write2_b32 v13, v72, v73 offset0:156 offset1:222
	v_add_u32_e32 v13, 0x1000, v54
	s_waitcnt vmcnt(16)
	ds_write2_b32 v13, v74, v75 offset0:32 offset1:98
	s_waitcnt vmcnt(14)
	ds_write2_b32 v13, v76, v77 offset0:164 offset1:230
	v_add_u32_e32 v13, 0x1400, v54
	s_waitcnt vmcnt(12)
	ds_write2_b32 v13, v78, v79 offset0:40 offset1:106
	s_waitcnt vmcnt(10)
	ds_write2_b32 v13, v80, v81 offset0:172 offset1:238
	v_add_u32_e32 v13, 0x1800, v54
	s_waitcnt vmcnt(8)
	ds_write2_b32 v13, v82, v83 offset0:48 offset1:114
	s_waitcnt vmcnt(6)
	ds_write2_b32 v13, v84, v85 offset0:180 offset1:246
	v_add_u32_e32 v13, 0x1c00, v54
	s_waitcnt vmcnt(4)
	ds_write2_b32 v13, v86, v87 offset0:56 offset1:122
	s_waitcnt vmcnt(2)
	ds_write2_b32 v13, v88, v89 offset0:188 offset1:254
	s_waitcnt lgkmcnt(0)
	v_lshl_add_u64 v[12:13], v[8:9], 0, s[2:3]
	s_waitcnt vmcnt(1)
; #define GAS __attribute__((address_space(1)))
; #define LAS __attribute__((address_space(3)))
; #define LDS_WAIT() asm volatile("s_waitcnt lgkmcnt(0)" ::: "memory")
; __device__ __forceinline__ void quant8_item(const float* W, int K, int N, signed char* WT, const gu32* wmax, LAS float* scr, int item, int lane) {
;     const int nblk = N / 32, kb = item / nblk, nb = item % nblk, k0 = 64 * kb, n0 = 32 * nb;
; #pragma unroll
;     for (int i = 0; i < 32; ++i) { const int kk = 2 * i + (lane >> 5); scr[kk * 33 + (lane & 31)] = W[(size_t)(k0 + kk) * N + n0 + (lane & 31)]; }
;     LDS_WAIT(); asm volatile("" ::: "memory");
;     const int c = lane & 3;
; #pragma unroll
;     for (int j = 0; j < 2; ++j) { const int n = (lane >> 2) + 16 * j; const LAS float* sp = scr + (16 * c) * 33 + n;
;         const float am = __builtin_bit_cast(float, __hip_atomic_load((unsigned*)(wmax + n0 + n), RLX_AGENT));
;         const float inv = 127.0f / fmaxf(am, 1e-30f);
;         unsigned w[4];
; #pragma unroll
;         for (int q = 0; q < 4; ++q) { unsigned pk = 0;
; #pragma unroll
;             for (int i = 0; i < 4; ++i) pk |= ((unsigned)(int)rintf(sp[(4 * q + i) * 33] * inv) & 0xffu) << (8 * i);
;             w[q] = pk; }
;         *(GAS u32x4*)(WT + (size_t)(n0 + n) * K + k0 + 16 * c) = (u32x4){w[0], w[1], w[2], w[3]}; }
;     LDS_WAIT(); asm volatile("" ::: "memory");
; }
	v_max_f32_e32 v2, v90, v90
	v_max_f32_e32 v2, 0xda24260, v2
	v_div_scale_f32 v3, s[2:3], v2, v2, s5
	v_rcp_f32_e32 v4, v3
	s_nop 0
	v_fma_f32 v5, -v3, v4, 1.0
	v_fmac_f32_e32 v4, v5, v4
	v_div_scale_f32 v5, vcc, s5, v2, s5
	v_mul_f32_e32 v16, v5, v4
	v_fma_f32 v17, -v3, v16, v5
	v_fmac_f32_e32 v16, v17, v4
	v_fma_f32 v3, -v3, v16, v5
	v_div_fmas_f32 v3, v3, v4, v16
	v_div_fixup_f32 v18, v3, v2, s5
	ds_read2_b32 v[2:3], v53 offset1:33
	s_waitcnt lgkmcnt(0)
	v_mul_f32_e32 v2, v2, v18
	v_rndne_f32_e32 v2, v2
	v_cvt_i32_f32_e32 v4, v2
	v_mul_f32_e32 v2, v3, v18
	v_rndne_f32_e32 v2, v2
	v_cvt_i32_f32_e32 v2, v2
	v_lshlrev_b32_e32 v5, 8, v2
	ds_read2_b32 v[2:3], v53 offset0:66 offset1:99
	v_perm_b32 v4, v5, v4, s16
	s_waitcnt lgkmcnt(0)
	v_mul_f32_e32 v2, v18, v2
	v_rndne_f32_e32 v2, v2
	v_mul_f32_e32 v3, v18, v3
	v_cvt_i32_f32_sdwa v2, v2 dst_sel:WORD_1 dst_unused:UNUSED_PAD src0_sel:DWORD
	v_rndne_f32_e32 v3, v3
	v_cvt_i32_f32_sdwa v3, v3 dst_sel:BYTE_3 dst_unused:UNUSED_PAD src0_sel:DWORD
	v_and_b32_e32 v2, 0xff0000, v2
	v_or3_b32 v2, v4, v2, v3
	ds_read2_b32 v[4:5], v53 offset0:132 offset1:165
	s_waitcnt lgkmcnt(0)
	v_mul_f32_e32 v3, v18, v4
	v_mul_f32_e32 v4, v18, v5
	v_rndne_f32_e32 v4, v4
	v_rndne_f32_e32 v3, v3
	v_cvt_i32_f32_e32 v4, v4
	v_cvt_i32_f32_e32 v3, v3
	v_lshlrev_b32_e32 v4, 8, v4
	v_perm_b32 v3, v4, v3, s16
	ds_read2_b32 v[4:5], v53 offset0:198 offset1:231
	s_waitcnt lgkmcnt(0)
	v_mul_f32_e32 v4, v18, v4
	v_rndne_f32_e32 v4, v4
	v_mul_f32_e32 v5, v18, v5
	v_cvt_i32_f32_sdwa v4, v4 dst_sel:WORD_1 dst_unused:UNUSED_PAD src0_sel:DWORD
	v_rndne_f32_e32 v5, v5
	v_cvt_i32_f32_sdwa v5, v5 dst_sel:BYTE_3 dst_unused:UNUSED_PAD src0_sel:DWORD
	v_and_b32_e32 v4, 0xff0000, v4
	v_or3_b32 v3, v3, v4, v5
	ds_read2_b32 v[4:5], v55 offset0:8 offset1:41
	s_waitcnt lgkmcnt(0)
	v_mul_f32_e32 v5, v18, v5
	v_mul_f32_e32 v4, v18, v4
	v_rndne_f32_e32 v5, v5
	v_rndne_f32_e32 v4, v4
	v_cvt_i32_f32_e32 v5, v5
	v_cvt_i32_f32_e32 v4, v4
	v_lshlrev_b32_e32 v5, 8, v5
	v_perm_b32 v16, v5, v4, s16
	ds_read2_b32 v[4:5], v55 offset0:74 offset1:107
	s_waitcnt lgkmcnt(0)
	v_mul_f32_e32 v4, v18, v4
	v_rndne_f32_e32 v4, v4
	v_mul_f32_e32 v5, v18, v5
	v_cvt_i32_f32_sdwa v4, v4 dst_sel:WORD_1 dst_unused:UNUSED_PAD src0_sel:DWORD
	v_rndne_f32_e32 v5, v5
	v_cvt_i32_f32_sdwa v5, v5 dst_sel:BYTE_3 dst_unused:UNUSED_PAD src0_sel:DWORD
	v_and_b32_e32 v4, 0xff0000, v4
	v_or3_b32 v4, v16, v4, v5
	ds_read2_b32 v[16:17], v55 offset0:140 offset1:173
	s_waitcnt lgkmcnt(0)
	v_mul_f32_e32 v5, v18, v16
	v_mul_f32_e32 v16, v18, v17
	v_rndne_f32_e32 v16, v16
	v_rndne_f32_e32 v5, v5
	v_cvt_i32_f32_e32 v16, v16
	v_cvt_i32_f32_e32 v5, v5
	v_lshlrev_b32_e32 v16, 8, v16
	v_perm_b32 v5, v16, v5, s16
	ds_read2_b32 v[16:17], v55 offset0:206 offset1:239
	s_waitcnt lgkmcnt(0)
	v_mul_f32_e32 v16, v18, v16
	v_rndne_f32_e32 v16, v16
	v_mul_f32_e32 v17, v18, v17
	v_cvt_i32_f32_sdwa v16, v16 dst_sel:WORD_1 dst_unused:UNUSED_PAD src0_sel:DWORD
	v_rndne_f32_e32 v17, v17
	v_cvt_i32_f32_sdwa v17, v17 dst_sel:BYTE_3 dst_unused:UNUSED_PAD src0_sel:DWORD
	v_and_b32_e32 v16, 0xff0000, v16
	v_or3_b32 v5, v5, v16, v17
	v_add_u32_e32 v16, s0, v52
	v_ashrrev_i32_e32 v17, 31, v16
	v_lshlrev_b64 v[18:19], 10, v[16:17]
	v_lshl_add_u64 v[18:19], v[12:13], 0, v[18:19]
	global_store_dwordx4 v[18:19], v[2:5], off
	s_nop 1
	s_waitcnt vmcnt(1)
	v_max_f32_e32 v2, v91, v91
	v_max_f32_e32 v2, 0xda24260, v2
	v_div_scale_f32 v3, s[0:1], v2, v2, s5
	v_rcp_f32_e32 v4, v3
	s_nop 0
	v_fma_f32 v5, -v3, v4, 1.0
	v_fmac_f32_e32 v4, v5, v4
	v_div_scale_f32 v5, vcc, s5, v2, s5
	v_mul_f32_e32 v14, v5, v4
	v_fma_f32 v15, -v3, v14, v5
	v_fmac_f32_e32 v14, v15, v4
	v_fma_f32 v3, -v3, v14, v5
	v_div_fmas_f32 v3, v3, v4, v14
	v_div_fixup_f32 v17, v3, v2, s5
	ds_read2_b32 v[2:3], v53 offset0:16 offset1:49
	s_waitcnt lgkmcnt(0)
	v_mul_f32_e32 v2, v2, v17
	v_rndne_f32_e32 v2, v2
	v_cvt_i32_f32_e32 v4, v2
	v_mul_f32_e32 v2, v3, v17
	v_rndne_f32_e32 v2, v2
	v_cvt_i32_f32_e32 v2, v2
	v_lshlrev_b32_e32 v5, 8, v2
	ds_read2_b32 v[2:3], v53 offset0:82 offset1:115
	v_perm_b32 v4, v5, v4, s16
	s_waitcnt lgkmcnt(0)
	v_mul_f32_e32 v2, v17, v2
	v_rndne_f32_e32 v2, v2
	v_mul_f32_e32 v3, v17, v3
	v_cvt_i32_f32_sdwa v2, v2 dst_sel:WORD_1 dst_unused:UNUSED_PAD src0_sel:DWORD
	v_rndne_f32_e32 v3, v3
	v_cvt_i32_f32_sdwa v3, v3 dst_sel:BYTE_3 dst_unused:UNUSED_PAD src0_sel:DWORD
	v_and_b32_e32 v2, 0xff0000, v2
	v_or3_b32 v2, v4, v2, v3
	ds_read2_b32 v[4:5], v53 offset0:148 offset1:181
	s_waitcnt lgkmcnt(0)
	v_mul_f32_e32 v3, v17, v4
	v_mul_f32_e32 v4, v17, v5
	v_rndne_f32_e32 v4, v4
	v_rndne_f32_e32 v3, v3
	v_cvt_i32_f32_e32 v4, v4
	v_cvt_i32_f32_e32 v3, v3
	v_lshlrev_b32_e32 v4, 8, v4
	v_perm_b32 v3, v4, v3, s16
	ds_read2_b32 v[4:5], v53 offset0:214 offset1:247
	s_waitcnt lgkmcnt(0)
	v_mul_f32_e32 v4, v17, v4
	v_rndne_f32_e32 v4, v4
	v_mul_f32_e32 v5, v17, v5
	v_cvt_i32_f32_sdwa v4, v4 dst_sel:WORD_1 dst_unused:UNUSED_PAD src0_sel:DWORD
	v_rndne_f32_e32 v5, v5
	v_cvt_i32_f32_sdwa v5, v5 dst_sel:BYTE_3 dst_unused:UNUSED_PAD src0_sel:DWORD
	v_and_b32_e32 v4, 0xff0000, v4
	v_or3_b32 v3, v3, v4, v5
	ds_read2_b32 v[4:5], v55 offset0:24 offset1:57
	s_waitcnt lgkmcnt(0)
	v_mul_f32_e32 v5, v17, v5
	v_mul_f32_e32 v4, v17, v4
	v_rndne_f32_e32 v5, v5
	v_rndne_f32_e32 v4, v4
	v_cvt_i32_f32_e32 v5, v5
	v_cvt_i32_f32_e32 v4, v4
	v_lshlrev_b32_e32 v5, 8, v5
	v_perm_b32 v14, v5, v4, s16
	ds_read2_b32 v[4:5], v55 offset0:90 offset1:123
	s_waitcnt lgkmcnt(0)
	v_mul_f32_e32 v4, v17, v4
	v_rndne_f32_e32 v4, v4
	v_mul_f32_e32 v5, v17, v5
	v_cvt_i32_f32_sdwa v4, v4 dst_sel:WORD_1 dst_unused:UNUSED_PAD src0_sel:DWORD
	v_rndne_f32_e32 v5, v5
	v_cvt_i32_f32_sdwa v5, v5 dst_sel:BYTE_3 dst_unused:UNUSED_PAD src0_sel:DWORD
	v_and_b32_e32 v4, 0xff0000, v4
	v_or3_b32 v4, v14, v4, v5
	ds_read2_b32 v[14:15], v55 offset0:156 offset1:189
	s_waitcnt lgkmcnt(0)
	v_mul_f32_e32 v5, v17, v14
	v_mul_f32_e32 v14, v17, v15
	v_rndne_f32_e32 v14, v14
	v_rndne_f32_e32 v5, v5
	v_cvt_i32_f32_e32 v14, v14
	v_cvt_i32_f32_e32 v5, v5
	v_lshlrev_b32_e32 v14, 8, v14
	v_perm_b32 v5, v14, v5, s16
	ds_read2_b32 v[14:15], v55 offset0:222 offset1:255
	s_waitcnt lgkmcnt(0)
	v_mul_f32_e32 v14, v17, v14
	v_rndne_f32_e32 v14, v14
	v_mul_f32_e32 v15, v17, v15
	v_cvt_i32_f32_sdwa v14, v14 dst_sel:WORD_1 dst_unused:UNUSED_PAD src0_sel:DWORD
	v_rndne_f32_e32 v15, v15
	v_cvt_i32_f32_sdwa v15, v15 dst_sel:BYTE_3 dst_unused:UNUSED_PAD src0_sel:DWORD
	v_and_b32_e32 v14, 0xff0000, v14
	v_or3_b32 v5, v5, v14, v15
	v_add_u32_e32 v14, 16, v16
	v_ashrrev_i32_e32 v15, 31, v14
	v_lshlrev_b64 v[14:15], 10, v[14:15]
	v_lshl_add_u64 v[12:13], v[12:13], 0, v[14:15]
	global_store_dwordx4 v[12:13], v[2:5], off
	s_waitcnt lgkmcnt(0)
	s_cbranch_scc1 .LBB0_1354
	s_mov_b64 s[50:51], s[42:43]
	s_mov_b32 s2, s26
	s_mov_b64 s[48:49], s[40:41]
	s_mov_b64 s[46:47], s[38:39]
	s_mov_b64 s[44:45], s[36:37]
	s_branch .LBB0_1357
